# GEMM K loops (proj/out/up/down): LDS-DMA prefetch issued at the top of each load block, before the LDS fragment reads (was after); on top of softmax max-tree cleanup
# baseline (speedup 1.0000x reference)
.LBB0_142:
	s_add_u32 s3, s6, 0xfffc0080
	s_addc_u32 s8, s7, -1
	s_cmp_eq_u32 s21, 12
	s_cselect_b32 s11, s17, s8
	s_cselect_b32 s10, s16, s3
	s_cselect_b32 s9, s2, s20
	s_cselect_b32 s8, s4, s5
	s_add_i32 s3, 0, 0x14000
	v_lshl_add_u64 v[186:187], s[6:7], 0, v[192:193]
	s_add_i32 m0, s54, 0xc000
	s_nop 0
	global_load_lds_dwordx4 v[186:187], off
	v_lshl_add_u64 v[186:187], s[6:7], 0, v[194:195]
	s_add_i32 m0, s54, 0xe000
	s_nop 0
	global_load_lds_dwordx4 v[186:187], off
	v_add_u32_e32 v106, s63, v17
	v_add_u32_e32 v162, s3, v17
	ds_read_b128 v[22:25], v106
	ds_read_b128 v[26:29], v106 offset:1024
	ds_read_b128 v[102:105], v106 offset:2048
	ds_read_b128 v[106:109], v106 offset:3072
	ds_read_b128 v[150:153], v162
	ds_read_b128 v[154:157], v162 offset:1024
	ds_read_b128 v[158:161], v162 offset:2048
	ds_read_b128 v[162:165], v162 offset:3072
	ds_read_b128 v[166:169], v247
	ds_read_b128 v[170:173], v247 offset:1024
	ds_read_b128 v[174:177], v247 offset:2048
	ds_read_b128 v[178:181], v247 offset:3072
	ds_read_b128 v[182:185], v247 offset:4096
	ds_read_b128 v[196:199], v247 offset:5120
	ds_read_b128 v[200:203], v247 offset:6144
	ds_read_b128 v[204:207], v247 offset:7168
	s_waitcnt vmcnt(8)
	s_waitcnt lgkmcnt(0)
	s_barrier
	s_setprio 1
	s_waitcnt lgkmcnt(0)
	v_mfma_f32_16x16x32_bf16 v[138:141], v[22:25], v[166:169], v[138:141]
	v_mfma_f32_16x16x32_bf16 v[98:101], v[102:105], v[166:169], v[98:101]
	v_mfma_f32_16x16x32_bf16 v[130:133], v[22:25], v[174:177], v[130:133]
	v_mfma_f32_16x16x32_bf16 v[90:93], v[102:105], v[174:177], v[90:93]
	v_mfma_f32_16x16x32_bf16 v[122:125], v[22:25], v[182:185], v[122:125]
	v_mfma_f32_16x16x32_bf16 v[82:85], v[102:105], v[182:185], v[82:85]
	v_mfma_f32_16x16x32_bf16 v[146:149], v[22:25], v[200:203], v[146:149]
	v_mfma_f32_16x16x32_bf16 v[110:113], v[102:105], v[200:203], v[110:113]
	v_mfma_f32_16x16x32_bf16 v[138:141], v[26:29], v[170:173], v[138:141]
	v_mfma_f32_16x16x32_bf16 v[98:101], v[106:109], v[170:173], v[98:101]
	v_mfma_f32_16x16x32_bf16 v[130:133], v[26:29], v[178:181], v[130:133]
	v_mfma_f32_16x16x32_bf16 v[90:93], v[106:109], v[178:181], v[90:93]
	v_mfma_f32_16x16x32_bf16 v[122:125], v[26:29], v[196:199], v[122:125]
	v_mfma_f32_16x16x32_bf16 v[82:85], v[106:109], v[196:199], v[82:85]
	v_mfma_f32_16x16x32_bf16 v[146:149], v[26:29], v[204:207], v[146:149]
	v_mfma_f32_16x16x32_bf16 v[110:113], v[106:109], v[204:207], v[110:113]
	s_setprio 0
	s_setprio 1
	v_mfma_f32_16x16x32_bf16 v[134:137], v[150:153], v[166:169], v[134:137]
	v_mfma_f32_16x16x32_bf16 v[94:97], v[158:161], v[166:169], v[94:97]
	v_mfma_f32_16x16x32_bf16 v[126:129], v[150:153], v[174:177], v[126:129]
	v_mfma_f32_16x16x32_bf16 v[86:89], v[158:161], v[174:177], v[86:89]
	v_mfma_f32_16x16x32_bf16 v[118:121], v[150:153], v[182:185], v[118:121]
	v_mfma_f32_16x16x32_bf16 v[78:81], v[158:161], v[182:185], v[78:81]
	v_mfma_f32_16x16x32_bf16 v[142:145], v[150:153], v[200:203], v[142:145]
	v_mfma_f32_16x16x32_bf16 v[114:117], v[158:161], v[200:203], v[114:117]
	v_mfma_f32_16x16x32_bf16 v[134:137], v[154:157], v[170:173], v[134:137]
	v_mfma_f32_16x16x32_bf16 v[94:97], v[162:165], v[170:173], v[94:97]
	v_mfma_f32_16x16x32_bf16 v[126:129], v[154:157], v[178:181], v[126:129]
	v_mfma_f32_16x16x32_bf16 v[86:89], v[162:165], v[178:181], v[86:89]
	v_mfma_f32_16x16x32_bf16 v[118:121], v[154:157], v[196:199], v[118:121]
	v_mfma_f32_16x16x32_bf16 v[78:81], v[162:165], v[196:199], v[78:81]
	v_mfma_f32_16x16x32_bf16 v[142:145], v[154:157], v[204:207], v[142:145]
	v_mfma_f32_16x16x32_bf16 v[114:117], v[162:165], v[204:207], v[114:117]
	s_setprio 0
	s_barrier
	s_add_i32 s24, s63, s1
	v_lshl_add_u64 v[186:187], s[8:9], 0, v[0:1]
	s_mov_b32 m0, s24
	s_nop 0
	global_load_lds_dwordx4 v[186:187], off
	s_add_i32 m0, s24, 0x2000
	s_add_u32 s24, s8, 0x40000
	v_lshl_add_u64 v[208:209], s[8:9], 0, v[14:15]
	s_addc_u32 s25, s9, 0
	s_add_i32 s3, s3, s1
	global_load_lds_dwordx4 v[208:209], off
	v_lshl_add_u64 v[210:211], s[24:25], 0, v[0:1]
	s_mov_b32 m0, s3
	v_lshl_add_u64 v[212:213], s[10:11], 0, v[188:189]
	global_load_lds_dwordx4 v[210:211], off
	v_lshl_add_u64 v[210:211], s[24:25], 0, v[14:15]
	s_add_i32 m0, s3, 0x2000
	s_nop 0
	global_load_lds_dwordx4 v[210:211], off
	v_lshl_add_u64 v[210:211], s[10:11], 0, v[190:191]
	s_mov_b32 m0, s54
	s_nop 0
	global_load_lds_dwordx4 v[210:211], off
	s_mov_b32 m0, s55
	s_nop 0
	global_load_lds_dwordx4 v[212:213], off
	ds_read_b128 v[166:169], v247 offset:16384
	ds_read_b128 v[170:173], v247 offset:17408
	ds_read_b128 v[174:177], v247 offset:18432
	ds_read_b128 v[178:181], v247 offset:19456
	ds_read_b128 v[182:185], v247 offset:20480
	ds_read_b128 v[196:199], v247 offset:21504
	ds_read_b128 v[200:203], v247 offset:22528
	ds_read_b128 v[204:207], v247 offset:23552
	s_waitcnt vmcnt(8)
	s_waitcnt lgkmcnt(0)
	s_barrier
	s_setprio 1
	s_waitcnt lgkmcnt(0)
	v_mfma_f32_16x16x32_bf16 v[74:77], v[22:25], v[166:169], v[74:77]
	v_mfma_f32_16x16x32_bf16 v[70:73], v[102:105], v[166:169], v[70:73]
	v_mfma_f32_16x16x32_bf16 v[66:69], v[22:25], v[174:177], v[66:69]
	v_mfma_f32_16x16x32_bf16 v[18:21], v[102:105], v[174:177], v[18:21]
	v_mfma_f32_16x16x32_bf16 v[54:57], v[22:25], v[182:185], v[54:57]
	v_mfma_f32_16x16x32_bf16 v[6:9], v[102:105], v[182:185], v[6:9]
	v_mfma_f32_16x16x32_bf16 v[22:25], v[22:25], v[200:203], v[42:45]
	v_mfma_f32_16x16x32_bf16 v[74:77], v[26:29], v[170:173], v[74:77]
	v_mfma_f32_16x16x32_bf16 v[70:73], v[106:109], v[170:173], v[70:73]
	v_mfma_f32_16x16x32_bf16 v[66:69], v[26:29], v[178:181], v[66:69]
	v_mfma_f32_16x16x32_bf16 v[18:21], v[106:109], v[178:181], v[18:21]
	v_mfma_f32_16x16x32_bf16 v[54:57], v[26:29], v[196:199], v[54:57]
	v_mfma_f32_16x16x32_bf16 v[6:9], v[106:109], v[196:199], v[6:9]
	v_mfma_f32_16x16x32_bf16 v[22:25], v[26:29], v[204:207], v[22:25]
	v_mfma_f32_16x16x32_bf16 v[26:29], v[102:105], v[200:203], v[30:33]
	v_mfma_f32_16x16x32_bf16 v[26:29], v[106:109], v[204:207], v[26:29]
	s_setprio 0
	s_setprio 1
	v_mfma_f32_16x16x32_bf16 v[30:33], v[150:153], v[166:169], v[62:65]
	v_mfma_f32_16x16x32_bf16 v[62:65], v[154:157], v[170:173], v[30:33]
	v_mfma_f32_16x16x32_bf16 v[30:33], v[158:161], v[166:169], v[58:61]
	v_mfma_f32_16x16x32_bf16 v[58:61], v[162:165], v[170:173], v[30:33]
	v_mfma_f32_16x16x32_bf16 v[30:33], v[150:153], v[174:177], v[50:53]
	v_mfma_f32_16x16x32_bf16 v[50:53], v[154:157], v[178:181], v[30:33]
	v_mfma_f32_16x16x32_bf16 v[30:33], v[150:153], v[182:185], v[46:49]
	v_mfma_f32_16x16x32_bf16 v[46:49], v[154:157], v[196:199], v[30:33]
	v_mfma_f32_16x16x32_bf16 v[30:33], v[150:153], v[200:203], v[38:41]
	v_mfma_f32_16x16x32_bf16 v[10:13], v[158:161], v[174:177], v[10:13]
	v_mfma_f32_16x16x32_bf16 v[2:5], v[158:161], v[182:185], v[2:5]
	v_mfma_f32_16x16x32_bf16 v[38:41], v[154:157], v[204:207], v[30:33]
	v_mfma_f32_16x16x32_bf16 v[30:33], v[158:161], v[200:203], v[34:37]
	v_mfma_f32_16x16x32_bf16 v[10:13], v[162:165], v[178:181], v[10:13]
	v_mfma_f32_16x16x32_bf16 v[2:5], v[162:165], v[196:199], v[2:5]
	v_mfma_f32_16x16x32_bf16 v[34:37], v[162:165], v[204:207], v[30:33]
	s_setprio 0
	s_barrier
	s_add_i32 s3, 0, 0x18000
	s_add_i32 s24, 0, 0x1c000
	s_add_u32 s10, s10, 0x40000
	s_addc_u32 s11, s11, 0
	s_mov_b32 m0, s74
	v_lshl_add_u64 v[218:219], s[10:11], 0, v[190:191]
	global_load_lds_dwordx4 v[218:219], off
	v_lshl_add_u64 v[218:219], s[10:11], 0, v[188:189]
	s_mov_b32 m0, s75
	s_nop 0
	global_load_lds_dwordx4 v[218:219], off
	v_add_u32_e32 v106, s3, v17
	v_add_u32_e32 v162, s24, v17
	ds_read_b128 v[30:33], v106
	ds_read_b128 v[42:45], v106 offset:1024
	ds_read_b128 v[102:105], v106 offset:2048
	ds_read_b128 v[106:109], v106 offset:3072
	ds_read_b128 v[150:153], v162
	ds_read_b128 v[154:157], v162 offset:1024
	ds_read_b128 v[158:161], v162 offset:2048
	ds_read_b128 v[162:165], v162 offset:3072
	ds_read_b128 v[166:169], v247 offset:32768
	ds_read_b128 v[170:173], v247 offset:33792
	ds_read_b128 v[174:177], v247 offset:34816
	ds_read_b128 v[178:181], v247 offset:35840
	ds_read_b128 v[182:185], v247 offset:36864
	ds_read_b128 v[196:199], v247 offset:37888
	ds_read_b128 v[200:203], v247 offset:38912
	ds_read_b128 v[204:207], v247 offset:39936
	s_waitcnt vmcnt(8)
	s_waitcnt lgkmcnt(0)
	s_barrier
	s_setprio 1
	s_waitcnt lgkmcnt(0)
	v_mfma_f32_16x16x32_bf16 v[138:141], v[30:33], v[166:169], v[138:141]
	v_mfma_f32_16x16x32_bf16 v[98:101], v[102:105], v[166:169], v[98:101]
	v_mfma_f32_16x16x32_bf16 v[130:133], v[30:33], v[174:177], v[130:133]
	v_mfma_f32_16x16x32_bf16 v[90:93], v[102:105], v[174:177], v[90:93]
	v_mfma_f32_16x16x32_bf16 v[122:125], v[30:33], v[182:185], v[122:125]
	v_mfma_f32_16x16x32_bf16 v[82:85], v[102:105], v[182:185], v[82:85]
	v_mfma_f32_16x16x32_bf16 v[146:149], v[30:33], v[200:203], v[146:149]
	v_mfma_f32_16x16x32_bf16 v[110:113], v[102:105], v[200:203], v[110:113]
	v_mfma_f32_16x16x32_bf16 v[138:141], v[42:45], v[170:173], v[138:141]
	v_mfma_f32_16x16x32_bf16 v[98:101], v[106:109], v[170:173], v[98:101]
	v_mfma_f32_16x16x32_bf16 v[130:133], v[42:45], v[178:181], v[130:133]
	v_mfma_f32_16x16x32_bf16 v[90:93], v[106:109], v[178:181], v[90:93]
	v_mfma_f32_16x16x32_bf16 v[122:125], v[42:45], v[196:199], v[122:125]
	v_mfma_f32_16x16x32_bf16 v[82:85], v[106:109], v[196:199], v[82:85]
	v_mfma_f32_16x16x32_bf16 v[146:149], v[42:45], v[204:207], v[146:149]
	v_mfma_f32_16x16x32_bf16 v[110:113], v[106:109], v[204:207], v[110:113]
	s_setprio 0
	s_setprio 1
	v_mfma_f32_16x16x32_bf16 v[134:137], v[150:153], v[166:169], v[134:137]
	v_mfma_f32_16x16x32_bf16 v[94:97], v[158:161], v[166:169], v[94:97]
	v_mfma_f32_16x16x32_bf16 v[126:129], v[150:153], v[174:177], v[126:129]
	v_mfma_f32_16x16x32_bf16 v[86:89], v[158:161], v[174:177], v[86:89]
	v_mfma_f32_16x16x32_bf16 v[118:121], v[150:153], v[182:185], v[118:121]
	v_mfma_f32_16x16x32_bf16 v[78:81], v[158:161], v[182:185], v[78:81]
	v_mfma_f32_16x16x32_bf16 v[142:145], v[150:153], v[200:203], v[142:145]
	v_mfma_f32_16x16x32_bf16 v[114:117], v[158:161], v[200:203], v[114:117]
	v_mfma_f32_16x16x32_bf16 v[134:137], v[154:157], v[170:173], v[134:137]
	v_mfma_f32_16x16x32_bf16 v[94:97], v[162:165], v[170:173], v[94:97]
	v_mfma_f32_16x16x32_bf16 v[126:129], v[154:157], v[178:181], v[126:129]
	v_mfma_f32_16x16x32_bf16 v[86:89], v[162:165], v[178:181], v[86:89]
	v_mfma_f32_16x16x32_bf16 v[118:121], v[154:157], v[196:199], v[118:121]
	v_mfma_f32_16x16x32_bf16 v[78:81], v[162:165], v[196:199], v[78:81]
	v_mfma_f32_16x16x32_bf16 v[142:145], v[154:157], v[204:207], v[142:145]
	v_mfma_f32_16x16x32_bf16 v[114:117], v[162:165], v[204:207], v[114:117]
	s_setprio 0
	s_barrier
	s_add_i32 s3, s3, s1
	v_lshl_add_u64 v[186:187], v[186:187], 0, s[92:93]
	s_mov_b32 m0, s3
	s_nop 0
	global_load_lds_dwordx4 v[186:187], off
	s_add_i32 m0, s3, 0x2000
	s_add_u32 s8, s8, 0x40080
	v_lshl_add_u64 v[186:187], v[208:209], 0, s[92:93]
	s_addc_u32 s9, s9, 0
	s_add_i32 s3, s24, s1
	global_load_lds_dwordx4 v[186:187], off
	v_lshl_add_u64 v[186:187], s[8:9], 0, v[0:1]
	s_mov_b32 m0, s3
	s_nop 0
	global_load_lds_dwordx4 v[186:187], off
	v_lshl_add_u64 v[186:187], s[8:9], 0, v[14:15]
	s_add_i32 m0, s3, 0x2000
	s_nop 0
	global_load_lds_dwordx4 v[186:187], off
	v_lshl_add_u64 v[186:187], v[210:211], 0, s[92:93]
	s_mov_b32 m0, s57
	s_nop 0
	global_load_lds_dwordx4 v[186:187], off
	v_lshl_add_u64 v[186:187], v[212:213], 0, s[92:93]
	s_mov_b32 m0, s58
	s_nop 0
	global_load_lds_dwordx4 v[186:187], off
	ds_read_b128 v[166:169], v247 offset:49152
	ds_read_b128 v[170:173], v247 offset:50176
	ds_read_b128 v[174:177], v247 offset:51200
	ds_read_b128 v[178:181], v247 offset:52224
	ds_read_b128 v[182:185], v247 offset:53248
	ds_read_b128 v[196:199], v247 offset:54272
	ds_read_b128 v[200:203], v247 offset:55296
	ds_read_b128 v[204:207], v247 offset:56320
	s_waitcnt vmcnt(8)
	s_waitcnt lgkmcnt(0)
	s_barrier
	s_setprio 1
	s_waitcnt lgkmcnt(0)
	v_mfma_f32_16x16x32_bf16 v[74:77], v[30:33], v[166:169], v[74:77]
	v_mfma_f32_16x16x32_bf16 v[66:69], v[30:33], v[174:177], v[66:69]
	v_mfma_f32_16x16x32_bf16 v[54:57], v[30:33], v[182:185], v[54:57]
	v_mfma_f32_16x16x32_bf16 v[22:25], v[30:33], v[200:203], v[22:25]
	v_mfma_f32_16x16x32_bf16 v[74:77], v[42:45], v[170:173], v[74:77]
	v_mfma_f32_16x16x32_bf16 v[70:73], v[102:105], v[166:169], v[70:73]
	v_mfma_f32_16x16x32_bf16 v[66:69], v[42:45], v[178:181], v[66:69]
	v_mfma_f32_16x16x32_bf16 v[18:21], v[102:105], v[174:177], v[18:21]
	v_mfma_f32_16x16x32_bf16 v[54:57], v[42:45], v[196:199], v[54:57]
	v_mfma_f32_16x16x32_bf16 v[6:9], v[102:105], v[182:185], v[6:9]
	v_mfma_f32_16x16x32_bf16 v[42:45], v[42:45], v[204:207], v[22:25]
	v_mfma_f32_16x16x32_bf16 v[22:25], v[102:105], v[200:203], v[26:29]
	v_mfma_f32_16x16x32_bf16 v[70:73], v[106:109], v[170:173], v[70:73]
	v_mfma_f32_16x16x32_bf16 v[18:21], v[106:109], v[178:181], v[18:21]
	v_mfma_f32_16x16x32_bf16 v[6:9], v[106:109], v[196:199], v[6:9]
	v_mfma_f32_16x16x32_bf16 v[30:33], v[106:109], v[204:207], v[22:25]
	s_setprio 0
	s_setprio 1
	v_mfma_f32_16x16x32_bf16 v[22:25], v[150:153], v[166:169], v[62:65]
	v_mfma_f32_16x16x32_bf16 v[62:65], v[154:157], v[170:173], v[22:25]
	v_mfma_f32_16x16x32_bf16 v[22:25], v[158:161], v[166:169], v[58:61]
	v_mfma_f32_16x16x32_bf16 v[58:61], v[162:165], v[170:173], v[22:25]
	v_mfma_f32_16x16x32_bf16 v[22:25], v[150:153], v[174:177], v[50:53]
	v_mfma_f32_16x16x32_bf16 v[50:53], v[154:157], v[178:181], v[22:25]
	v_mfma_f32_16x16x32_bf16 v[22:25], v[150:153], v[182:185], v[46:49]
	v_mfma_f32_16x16x32_bf16 v[46:49], v[154:157], v[196:199], v[22:25]
	v_mfma_f32_16x16x32_bf16 v[22:25], v[150:153], v[200:203], v[38:41]
	v_mfma_f32_16x16x32_bf16 v[10:13], v[158:161], v[174:177], v[10:13]
	v_mfma_f32_16x16x32_bf16 v[2:5], v[158:161], v[182:185], v[2:5]
	v_mfma_f32_16x16x32_bf16 v[38:41], v[154:157], v[204:207], v[22:25]
	v_mfma_f32_16x16x32_bf16 v[22:25], v[158:161], v[200:203], v[34:37]
	v_mfma_f32_16x16x32_bf16 v[10:13], v[162:165], v[178:181], v[10:13]
	v_mfma_f32_16x16x32_bf16 v[2:5], v[162:165], v[196:199], v[2:5]
	v_mfma_f32_16x16x32_bf16 v[34:37], v[162:165], v[204:207], v[22:25]
	s_setprio 0
	s_barrier
	s_add_i32 s21, s21, 2
	s_add_u32 s6, s6, 0x100
	s_addc_u32 s7, s7, 0
	s_add_u32 s5, s5, 0x100
	s_addc_u32 s20, s20, 0
	s_cmp_gt_u32 s21, 13
	s_cbranch_scc0 .LBB0_142
	v_readlane_b32 s2, v255, 51
	v_readlane_b32 s3, v255, 52
	s_and_b64 vcc, exec, s[2:3]
	s_cbranch_vccz .LBB0_145
	s_barrier

.LBB0_192:
	s_add_u32 s3, s6, 0xfffc0080
	s_addc_u32 s8, s7, -1
	s_cmp_eq_u32 vcc_lo, 12
	s_cselect_b32 s37, s38, s8
	s_cselect_b32 s36, s39, s3
	s_cselect_b32 s9, s2, s84
	s_cselect_b32 s8, s43, s45
	s_add_i32 s3, 0, 0x14000
	v_lshl_add_u64 v[202:203], s[6:7], 0, v[182:183]
	s_add_i32 m0, s50, 0xc000
	s_nop 0
	global_load_lds_dwordx4 v[202:203], off
	v_lshl_add_u64 v[202:203], s[6:7], 0, v[184:185]
	s_add_i32 m0, s50, 0xe000
	s_nop 0
	global_load_lds_dwordx4 v[202:203], off
	v_add_u32_e32 v70, s63, v17
	v_add_u32_e32 v162, s3, v17
	ds_read_b128 v[54:57], v70
	ds_read_b128 v[58:61], v70 offset:1024
	ds_read_b128 v[62:65], v70 offset:2048
	ds_read_b128 v[70:73], v70 offset:3072
	ds_read_b128 v[150:153], v162
	ds_read_b128 v[154:157], v162 offset:1024
	ds_read_b128 v[158:161], v162 offset:2048
	ds_read_b128 v[162:165], v162 offset:3072
	ds_read_b128 v[166:169], v224
	ds_read_b128 v[170:173], v224 offset:1024
	ds_read_b128 v[174:177], v224 offset:2048
	ds_read_b128 v[178:181], v224 offset:3072
	ds_read_b128 v[186:189], v224 offset:4096
	ds_read_b128 v[190:193], v224 offset:5120
	ds_read_b128 v[194:197], v224 offset:6144
	ds_read_b128 v[198:201], v224 offset:7168
	s_waitcnt vmcnt(8)
	s_waitcnt lgkmcnt(0)
	s_barrier
	s_setprio 1
	s_waitcnt lgkmcnt(0)
	v_mfma_f32_16x16x32_bf16 v[146:149], v[54:57], v[166:169], v[146:149]
	v_mfma_f32_16x16x32_bf16 v[142:145], v[62:65], v[166:169], v[142:145]
	v_mfma_f32_16x16x32_bf16 v[130:133], v[54:57], v[174:177], v[130:133]
	v_mfma_f32_16x16x32_bf16 v[126:129], v[62:65], v[174:177], v[126:129]
	v_mfma_f32_16x16x32_bf16 v[114:117], v[54:57], v[186:189], v[114:117]
	v_mfma_f32_16x16x32_bf16 v[110:113], v[62:65], v[186:189], v[110:113]
	v_mfma_f32_16x16x32_bf16 v[98:101], v[54:57], v[194:197], v[98:101]
	v_mfma_f32_16x16x32_bf16 v[94:97], v[62:65], v[194:197], v[94:97]
	v_mfma_f32_16x16x32_bf16 v[146:149], v[58:61], v[170:173], v[146:149]
	v_mfma_f32_16x16x32_bf16 v[142:145], v[70:73], v[170:173], v[142:145]
	v_mfma_f32_16x16x32_bf16 v[130:133], v[58:61], v[178:181], v[130:133]
	v_mfma_f32_16x16x32_bf16 v[126:129], v[70:73], v[178:181], v[126:129]
	v_mfma_f32_16x16x32_bf16 v[114:117], v[58:61], v[190:193], v[114:117]
	v_mfma_f32_16x16x32_bf16 v[110:113], v[70:73], v[190:193], v[110:113]
	v_mfma_f32_16x16x32_bf16 v[98:101], v[58:61], v[198:201], v[98:101]
	v_mfma_f32_16x16x32_bf16 v[94:97], v[70:73], v[198:201], v[94:97]
	s_setprio 0
	s_setprio 1
	v_mfma_f32_16x16x32_bf16 v[138:141], v[150:153], v[166:169], v[138:141]
	v_mfma_f32_16x16x32_bf16 v[134:137], v[158:161], v[166:169], v[134:137]
	v_mfma_f32_16x16x32_bf16 v[122:125], v[150:153], v[174:177], v[122:125]
	v_mfma_f32_16x16x32_bf16 v[118:121], v[158:161], v[174:177], v[118:121]
	v_mfma_f32_16x16x32_bf16 v[106:109], v[150:153], v[186:189], v[106:109]
	v_mfma_f32_16x16x32_bf16 v[102:105], v[158:161], v[186:189], v[102:105]
	v_mfma_f32_16x16x32_bf16 v[90:93], v[150:153], v[194:197], v[90:93]
	v_mfma_f32_16x16x32_bf16 v[86:89], v[158:161], v[194:197], v[86:89]
	v_mfma_f32_16x16x32_bf16 v[138:141], v[154:157], v[170:173], v[138:141]
	v_mfma_f32_16x16x32_bf16 v[134:137], v[162:165], v[170:173], v[134:137]
	v_mfma_f32_16x16x32_bf16 v[122:125], v[154:157], v[178:181], v[122:125]
	v_mfma_f32_16x16x32_bf16 v[118:121], v[162:165], v[178:181], v[118:121]
	v_mfma_f32_16x16x32_bf16 v[106:109], v[154:157], v[190:193], v[106:109]
	v_mfma_f32_16x16x32_bf16 v[102:105], v[162:165], v[190:193], v[102:105]
	v_mfma_f32_16x16x32_bf16 v[90:93], v[154:157], v[198:201], v[90:93]
	v_mfma_f32_16x16x32_bf16 v[86:89], v[162:165], v[198:201], v[86:89]
	s_setprio 0
	s_barrier
	s_add_i32 s24, s63, s41
	v_lshl_add_u64 v[202:203], s[8:9], 0, v[0:1]
	s_mov_b32 m0, s24
	s_nop 0
	global_load_lds_dwordx4 v[202:203], off
	s_add_i32 m0, s24, 0x2000
	s_add_u32 s24, s8, 0x40000
	v_lshl_add_u64 v[204:205], s[8:9], 0, v[14:15]
	s_addc_u32 s25, s9, 0
	s_add_i32 s3, s3, s41
	global_load_lds_dwordx4 v[204:205], off
	v_lshl_add_u64 v[206:207], s[24:25], 0, v[0:1]
	s_mov_b32 m0, s3
	v_lshl_add_u64 v[208:209], s[36:37], 0, v[14:15]
	global_load_lds_dwordx4 v[206:207], off
	v_lshl_add_u64 v[206:207], s[24:25], 0, v[14:15]
	s_add_i32 m0, s3, 0x2000
	s_nop 0
	global_load_lds_dwordx4 v[206:207], off
	v_lshl_add_u64 v[206:207], s[36:37], 0, v[0:1]
	s_mov_b32 m0, s50
	s_nop 0
	global_load_lds_dwordx4 v[206:207], off
	s_mov_b32 m0, s51
	s_nop 0
	global_load_lds_dwordx4 v[208:209], off
	ds_read_b128 v[166:169], v224 offset:16384
	ds_read_b128 v[170:173], v224 offset:17408
	ds_read_b128 v[174:177], v224 offset:18432
	ds_read_b128 v[178:181], v224 offset:19456
	ds_read_b128 v[186:189], v224 offset:20480
	ds_read_b128 v[190:193], v224 offset:21504
	ds_read_b128 v[194:197], v224 offset:22528
	ds_read_b128 v[198:201], v224 offset:23552
	s_waitcnt vmcnt(8)
	s_waitcnt lgkmcnt(0)
	s_barrier
	s_setprio 1
	s_waitcnt lgkmcnt(0)
	v_mfma_f32_16x16x32_bf16 v[82:85], v[54:57], v[166:169], v[82:85]
	v_mfma_f32_16x16x32_bf16 v[78:81], v[62:65], v[166:169], v[78:81]
	v_mfma_f32_16x16x32_bf16 v[50:53], v[54:57], v[174:177], v[50:53]
	v_mfma_f32_16x16x32_bf16 v[46:49], v[62:65], v[174:177], v[46:49]
	v_mfma_f32_16x16x32_bf16 v[34:37], v[54:57], v[186:189], v[34:37]
	v_mfma_f32_16x16x32_bf16 v[30:33], v[62:65], v[186:189], v[30:33]
	v_mfma_f32_16x16x32_bf16 v[18:21], v[54:57], v[194:197], v[18:21]
	v_mfma_f32_16x16x32_bf16 v[10:13], v[62:65], v[194:197], v[10:13]
	v_mfma_f32_16x16x32_bf16 v[82:85], v[58:61], v[170:173], v[82:85]
	v_mfma_f32_16x16x32_bf16 v[78:81], v[70:73], v[170:173], v[78:81]
	v_mfma_f32_16x16x32_bf16 v[50:53], v[58:61], v[178:181], v[50:53]
	v_mfma_f32_16x16x32_bf16 v[46:49], v[70:73], v[178:181], v[46:49]
	v_mfma_f32_16x16x32_bf16 v[34:37], v[58:61], v[190:193], v[34:37]
	v_mfma_f32_16x16x32_bf16 v[30:33], v[70:73], v[190:193], v[30:33]
	v_mfma_f32_16x16x32_bf16 v[18:21], v[58:61], v[198:201], v[18:21]
	v_mfma_f32_16x16x32_bf16 v[10:13], v[70:73], v[198:201], v[10:13]
	s_setprio 0
	s_setprio 1
	v_mfma_f32_16x16x32_bf16 v[42:45], v[150:153], v[174:177], v[42:45]
	v_mfma_f32_16x16x32_bf16 v[38:41], v[158:161], v[174:177], v[38:41]
	v_mfma_f32_16x16x32_bf16 v[26:29], v[150:153], v[186:189], v[26:29]
	v_mfma_f32_16x16x32_bf16 v[22:25], v[158:161], v[186:189], v[22:25]
	v_mfma_f32_16x16x32_bf16 v[6:9], v[150:153], v[194:197], v[6:9]
	v_mfma_f32_16x16x32_bf16 v[2:5], v[158:161], v[194:197], v[2:5]
	v_mfma_f32_16x16x32_bf16 v[54:57], v[150:153], v[166:169], v[74:77]
	v_mfma_f32_16x16x32_bf16 v[58:61], v[158:161], v[166:169], v[66:69]
	v_mfma_f32_16x16x32_bf16 v[42:45], v[154:157], v[178:181], v[42:45]
	v_mfma_f32_16x16x32_bf16 v[38:41], v[162:165], v[178:181], v[38:41]
	v_mfma_f32_16x16x32_bf16 v[26:29], v[154:157], v[190:193], v[26:29]
	v_mfma_f32_16x16x32_bf16 v[22:25], v[162:165], v[190:193], v[22:25]
	v_mfma_f32_16x16x32_bf16 v[6:9], v[154:157], v[198:201], v[6:9]
	v_mfma_f32_16x16x32_bf16 v[2:5], v[162:165], v[198:201], v[2:5]
	v_mfma_f32_16x16x32_bf16 v[54:57], v[154:157], v[170:173], v[54:57]
	v_mfma_f32_16x16x32_bf16 v[58:61], v[162:165], v[170:173], v[58:61]
	s_setprio 0
	s_barrier
	s_add_i32 s3, 0, 0x18000
	s_add_i32 s26, 0, 0x1c000
	s_add_u32 s24, s36, 0x40000
	s_addc_u32 s25, s37, 0
	s_mov_b32 m0, s52
	v_lshl_add_u64 v[210:211], s[24:25], 0, v[0:1]
	global_load_lds_dwordx4 v[210:211], off
	v_lshl_add_u64 v[210:211], s[24:25], 0, v[14:15]
	s_mov_b32 m0, s53
	s_nop 0
	global_load_lds_dwordx4 v[210:211], off
	v_add_u32_e32 v74, s3, v17
	v_add_u32_e32 v162, s26, v17
	ds_read_b128 v[62:65], v74
	ds_read_b128 v[66:69], v74 offset:1024
	ds_read_b128 v[70:73], v74 offset:2048
	ds_read_b128 v[74:77], v74 offset:3072
	ds_read_b128 v[150:153], v162
	ds_read_b128 v[154:157], v162 offset:1024
	ds_read_b128 v[158:161], v162 offset:2048
	ds_read_b128 v[162:165], v162 offset:3072
	ds_read_b128 v[166:169], v224 offset:32768
	ds_read_b128 v[170:173], v224 offset:33792
	ds_read_b128 v[174:177], v224 offset:34816
	ds_read_b128 v[178:181], v224 offset:35840
	ds_read_b128 v[186:189], v224 offset:36864
	ds_read_b128 v[190:193], v224 offset:37888
	ds_read_b128 v[194:197], v224 offset:38912
	ds_read_b128 v[198:201], v224 offset:39936
	s_waitcnt vmcnt(8)
	s_waitcnt lgkmcnt(0)
	s_barrier
	s_setprio 1
	s_waitcnt lgkmcnt(0)
	v_mfma_f32_16x16x32_bf16 v[146:149], v[62:65], v[166:169], v[146:149]
	v_mfma_f32_16x16x32_bf16 v[142:145], v[70:73], v[166:169], v[142:145]
	v_mfma_f32_16x16x32_bf16 v[130:133], v[62:65], v[174:177], v[130:133]
	v_mfma_f32_16x16x32_bf16 v[126:129], v[70:73], v[174:177], v[126:129]
	v_mfma_f32_16x16x32_bf16 v[114:117], v[62:65], v[186:189], v[114:117]
	v_mfma_f32_16x16x32_bf16 v[110:113], v[70:73], v[186:189], v[110:113]
	v_mfma_f32_16x16x32_bf16 v[98:101], v[62:65], v[194:197], v[98:101]
	v_mfma_f32_16x16x32_bf16 v[94:97], v[70:73], v[194:197], v[94:97]
	v_mfma_f32_16x16x32_bf16 v[146:149], v[66:69], v[170:173], v[146:149]
	v_mfma_f32_16x16x32_bf16 v[142:145], v[74:77], v[170:173], v[142:145]
	v_mfma_f32_16x16x32_bf16 v[130:133], v[66:69], v[178:181], v[130:133]
	v_mfma_f32_16x16x32_bf16 v[126:129], v[74:77], v[178:181], v[126:129]
	v_mfma_f32_16x16x32_bf16 v[114:117], v[66:69], v[190:193], v[114:117]
	v_mfma_f32_16x16x32_bf16 v[110:113], v[74:77], v[190:193], v[110:113]
	v_mfma_f32_16x16x32_bf16 v[98:101], v[66:69], v[198:201], v[98:101]
	v_mfma_f32_16x16x32_bf16 v[94:97], v[74:77], v[198:201], v[94:97]
	s_setprio 0
	s_setprio 1
	v_mfma_f32_16x16x32_bf16 v[138:141], v[150:153], v[166:169], v[138:141]
	v_mfma_f32_16x16x32_bf16 v[134:137], v[158:161], v[166:169], v[134:137]
	v_mfma_f32_16x16x32_bf16 v[122:125], v[150:153], v[174:177], v[122:125]
	v_mfma_f32_16x16x32_bf16 v[118:121], v[158:161], v[174:177], v[118:121]
	v_mfma_f32_16x16x32_bf16 v[106:109], v[150:153], v[186:189], v[106:109]
	v_mfma_f32_16x16x32_bf16 v[102:105], v[158:161], v[186:189], v[102:105]
	v_mfma_f32_16x16x32_bf16 v[90:93], v[150:153], v[194:197], v[90:93]
	v_mfma_f32_16x16x32_bf16 v[86:89], v[158:161], v[194:197], v[86:89]
	v_mfma_f32_16x16x32_bf16 v[138:141], v[154:157], v[170:173], v[138:141]
	v_mfma_f32_16x16x32_bf16 v[134:137], v[162:165], v[170:173], v[134:137]
	v_mfma_f32_16x16x32_bf16 v[122:125], v[154:157], v[178:181], v[122:125]
	v_mfma_f32_16x16x32_bf16 v[118:121], v[162:165], v[178:181], v[118:121]
	v_mfma_f32_16x16x32_bf16 v[106:109], v[154:157], v[190:193], v[106:109]
	v_mfma_f32_16x16x32_bf16 v[102:105], v[162:165], v[190:193], v[102:105]
	v_mfma_f32_16x16x32_bf16 v[90:93], v[154:157], v[198:201], v[90:93]
	v_mfma_f32_16x16x32_bf16 v[86:89], v[162:165], v[198:201], v[86:89]
	s_setprio 0
	s_barrier
	s_add_i32 s3, s3, s41
	v_lshl_add_u64 v[202:203], v[202:203], 0, s[92:93]
	s_mov_b32 m0, s3
	s_nop 0
	global_load_lds_dwordx4 v[202:203], off
	s_add_i32 m0, s3, 0x2000
	s_add_u32 s8, s8, 0x40080
	v_lshl_add_u64 v[202:203], v[204:205], 0, s[92:93]
	s_addc_u32 s9, s9, 0
	s_add_i32 s3, s26, s41
	global_load_lds_dwordx4 v[202:203], off
	v_lshl_add_u64 v[202:203], s[8:9], 0, v[0:1]
	s_mov_b32 m0, s3
	s_nop 0
	global_load_lds_dwordx4 v[202:203], off
	v_lshl_add_u64 v[202:203], s[8:9], 0, v[14:15]
	s_add_i32 m0, s3, 0x2000
	s_nop 0
	global_load_lds_dwordx4 v[202:203], off
	v_lshl_add_u64 v[202:203], v[206:207], 0, s[92:93]
	s_mov_b32 m0, s59
	s_nop 0
	global_load_lds_dwordx4 v[202:203], off
	v_lshl_add_u64 v[202:203], v[208:209], 0, s[92:93]
	s_mov_b32 m0, s74
	s_nop 0
	global_load_lds_dwordx4 v[202:203], off
	ds_read_b128 v[166:169], v224 offset:49152
	ds_read_b128 v[170:173], v224 offset:50176
	ds_read_b128 v[174:177], v224 offset:51200
	ds_read_b128 v[178:181], v224 offset:52224
	ds_read_b128 v[186:189], v224 offset:53248
	ds_read_b128 v[190:193], v224 offset:54272
	ds_read_b128 v[194:197], v224 offset:55296
	ds_read_b128 v[198:201], v224 offset:56320
	s_waitcnt vmcnt(8)
	s_waitcnt lgkmcnt(0)
	s_barrier
	s_setprio 1
	s_waitcnt lgkmcnt(0)
	v_mfma_f32_16x16x32_bf16 v[82:85], v[62:65], v[166:169], v[82:85]
	v_mfma_f32_16x16x32_bf16 v[78:81], v[70:73], v[166:169], v[78:81]
	v_mfma_f32_16x16x32_bf16 v[50:53], v[62:65], v[174:177], v[50:53]
	v_mfma_f32_16x16x32_bf16 v[46:49], v[70:73], v[174:177], v[46:49]
	v_mfma_f32_16x16x32_bf16 v[34:37], v[62:65], v[186:189], v[34:37]
	v_mfma_f32_16x16x32_bf16 v[30:33], v[70:73], v[186:189], v[30:33]
	v_mfma_f32_16x16x32_bf16 v[18:21], v[62:65], v[194:197], v[18:21]
	v_mfma_f32_16x16x32_bf16 v[10:13], v[70:73], v[194:197], v[10:13]
	v_mfma_f32_16x16x32_bf16 v[82:85], v[66:69], v[170:173], v[82:85]
	v_mfma_f32_16x16x32_bf16 v[78:81], v[74:77], v[170:173], v[78:81]
	v_mfma_f32_16x16x32_bf16 v[50:53], v[66:69], v[178:181], v[50:53]
	v_mfma_f32_16x16x32_bf16 v[46:49], v[74:77], v[178:181], v[46:49]
	v_mfma_f32_16x16x32_bf16 v[34:37], v[66:69], v[190:193], v[34:37]
	v_mfma_f32_16x16x32_bf16 v[30:33], v[74:77], v[190:193], v[30:33]
	v_mfma_f32_16x16x32_bf16 v[18:21], v[66:69], v[198:201], v[18:21]
	v_mfma_f32_16x16x32_bf16 v[10:13], v[74:77], v[198:201], v[10:13]
	s_setprio 0
	s_setprio 1
	v_mfma_f32_16x16x32_bf16 v[54:57], v[150:153], v[166:169], v[54:57]
	v_mfma_f32_16x16x32_bf16 v[74:77], v[154:157], v[170:173], v[54:57]
	v_mfma_f32_16x16x32_bf16 v[54:57], v[158:161], v[166:169], v[58:61]
	v_mfma_f32_16x16x32_bf16 v[42:45], v[150:153], v[174:177], v[42:45]
	v_mfma_f32_16x16x32_bf16 v[38:41], v[158:161], v[174:177], v[38:41]
	v_mfma_f32_16x16x32_bf16 v[26:29], v[150:153], v[186:189], v[26:29]
	v_mfma_f32_16x16x32_bf16 v[22:25], v[158:161], v[186:189], v[22:25]
	v_mfma_f32_16x16x32_bf16 v[6:9], v[150:153], v[194:197], v[6:9]
	v_mfma_f32_16x16x32_bf16 v[2:5], v[158:161], v[194:197], v[2:5]
	v_mfma_f32_16x16x32_bf16 v[66:69], v[162:165], v[170:173], v[54:57]
	v_mfma_f32_16x16x32_bf16 v[42:45], v[154:157], v[178:181], v[42:45]
	v_mfma_f32_16x16x32_bf16 v[38:41], v[162:165], v[178:181], v[38:41]
	v_mfma_f32_16x16x32_bf16 v[26:29], v[154:157], v[190:193], v[26:29]
	v_mfma_f32_16x16x32_bf16 v[22:25], v[162:165], v[190:193], v[22:25]
	v_mfma_f32_16x16x32_bf16 v[6:9], v[154:157], v[198:201], v[6:9]
	v_mfma_f32_16x16x32_bf16 v[2:5], v[162:165], v[198:201], v[2:5]
	s_setprio 0
	s_barrier
	s_add_i32 vcc_lo, vcc_lo, 2
	s_add_u32 s6, s6, 0x100
	s_addc_u32 s7, s7, 0
	s_add_u32 s45, s45, 0x100
	s_addc_u32 s84, s84, 0
	s_cmp_gt_u32 vcc_lo, 13
	s_cbranch_scc0 .LBB0_192
	s_and_b64 vcc, exec, s[18:19]
	s_cbranch_vccz .LBB0_195
	s_barrier

.LBB0_751:
	s_add_u32 s6, s22, 0x100
	s_addc_u32 s7, s23, 0
	s_cmp_eq_u32 s57, 40
	s_cselect_b32 s39, s17, s7
	s_cselect_b32 s38, s16, s6
	s_cselect_b32 s37, s19, s55
	s_cselect_b32 s36, s18, s2
	s_add_i32 s3, 0, 0x14000
	v_lshl_add_u64 v[198:199], s[22:23], 0, v[222:223]
	s_add_i32 m0, s42, 0xc000
	s_nop 0
	global_load_lds_dwordx4 v[198:199], off
	v_lshl_add_u64 v[198:199], s[22:23], 0, v[224:225]
	s_add_i32 m0, s42, 0xe000
	s_nop 0
	global_load_lds_dwordx4 v[198:199], off
	v_add_u32_e32 v82, s63, v17
	v_add_u32_e32 v162, s3, v17
	ds_read_b128 v[70:73], v82
	ds_read_b128 v[74:77], v82 offset:1024
	ds_read_b128 v[78:81], v82 offset:2048
	ds_read_b128 v[82:85], v82 offset:3072
	ds_read_b128 v[150:153], v162
	ds_read_b128 v[154:157], v162 offset:1024
	ds_read_b128 v[158:161], v162 offset:2048
	ds_read_b128 v[162:165], v162 offset:3072
	ds_read_b128 v[166:169], v242
	ds_read_b128 v[170:173], v242 offset:1024
	ds_read_b128 v[174:177], v242 offset:2048
	ds_read_b128 v[178:181], v242 offset:3072
	ds_read_b128 v[182:185], v242 offset:4096
	ds_read_b128 v[186:189], v242 offset:5120
	ds_read_b128 v[190:193], v242 offset:6144
	ds_read_b128 v[194:197], v242 offset:7168
	s_waitcnt vmcnt(8)
	s_waitcnt lgkmcnt(0)
	s_barrier
	s_setprio 1
	s_waitcnt lgkmcnt(0)
	v_mfma_f32_16x16x32_bf16 v[146:149], v[70:73], v[166:169], v[146:149]
	v_mfma_f32_16x16x32_bf16 v[142:145], v[78:81], v[166:169], v[142:145]
	v_mfma_f32_16x16x32_bf16 v[130:133], v[70:73], v[174:177], v[130:133]
	v_mfma_f32_16x16x32_bf16 v[126:129], v[78:81], v[174:177], v[126:129]
	v_mfma_f32_16x16x32_bf16 v[114:117], v[70:73], v[182:185], v[114:117]
	v_mfma_f32_16x16x32_bf16 v[110:113], v[78:81], v[182:185], v[110:113]
	v_mfma_f32_16x16x32_bf16 v[98:101], v[70:73], v[190:193], v[98:101]
	v_mfma_f32_16x16x32_bf16 v[94:97], v[78:81], v[190:193], v[94:97]
	v_mfma_f32_16x16x32_bf16 v[146:149], v[74:77], v[170:173], v[146:149]
	v_mfma_f32_16x16x32_bf16 v[142:145], v[82:85], v[170:173], v[142:145]
	v_mfma_f32_16x16x32_bf16 v[130:133], v[74:77], v[178:181], v[130:133]
	v_mfma_f32_16x16x32_bf16 v[126:129], v[82:85], v[178:181], v[126:129]
	v_mfma_f32_16x16x32_bf16 v[114:117], v[74:77], v[186:189], v[114:117]
	v_mfma_f32_16x16x32_bf16 v[110:113], v[82:85], v[186:189], v[110:113]
	v_mfma_f32_16x16x32_bf16 v[98:101], v[74:77], v[194:197], v[98:101]
	v_mfma_f32_16x16x32_bf16 v[94:97], v[82:85], v[194:197], v[94:97]
	s_setprio 0
	s_setprio 1
	v_mfma_f32_16x16x32_bf16 v[138:141], v[150:153], v[166:169], v[138:141]
	v_mfma_f32_16x16x32_bf16 v[134:137], v[158:161], v[166:169], v[134:137]
	v_mfma_f32_16x16x32_bf16 v[122:125], v[150:153], v[174:177], v[122:125]
	v_mfma_f32_16x16x32_bf16 v[118:121], v[158:161], v[174:177], v[118:121]
	v_mfma_f32_16x16x32_bf16 v[106:109], v[150:153], v[182:185], v[106:109]
	v_mfma_f32_16x16x32_bf16 v[102:105], v[158:161], v[182:185], v[102:105]
	v_mfma_f32_16x16x32_bf16 v[90:93], v[150:153], v[190:193], v[90:93]
	v_mfma_f32_16x16x32_bf16 v[86:89], v[158:161], v[190:193], v[86:89]
	v_mfma_f32_16x16x32_bf16 v[138:141], v[154:157], v[170:173], v[138:141]
	v_mfma_f32_16x16x32_bf16 v[134:137], v[162:165], v[170:173], v[134:137]
	v_mfma_f32_16x16x32_bf16 v[122:125], v[154:157], v[178:181], v[122:125]
	v_mfma_f32_16x16x32_bf16 v[118:121], v[162:165], v[178:181], v[118:121]
	v_mfma_f32_16x16x32_bf16 v[106:109], v[154:157], v[186:189], v[106:109]
	v_mfma_f32_16x16x32_bf16 v[102:105], v[162:165], v[186:189], v[102:105]
	v_mfma_f32_16x16x32_bf16 v[90:93], v[154:157], v[194:197], v[90:93]
	v_mfma_f32_16x16x32_bf16 v[86:89], v[162:165], v[194:197], v[86:89]
	s_setprio 0
	s_barrier
	s_add_i32 s22, s63, s41
	v_lshl_add_u64 v[198:199], s[36:37], 0, v[0:1]
	s_mov_b32 m0, s22
	s_nop 0
	global_load_lds_dwordx4 v[198:199], off
	s_add_i32 m0, s22, 0x2000
	s_add_u32 s22, s36, 0xb0000
	v_lshl_add_u64 v[200:201], s[36:37], 0, v[14:15]
	s_addc_u32 s23, s37, 0
	s_add_i32 s3, s3, s41
	global_load_lds_dwordx4 v[200:201], off
	v_lshl_add_u64 v[202:203], s[22:23], 0, v[0:1]
	s_mov_b32 m0, s3
	v_lshl_add_u64 v[204:205], s[38:39], 0, v[14:15]
	global_load_lds_dwordx4 v[202:203], off
	v_lshl_add_u64 v[202:203], s[22:23], 0, v[14:15]
	s_add_i32 m0, s3, 0x2000
	s_nop 0
	global_load_lds_dwordx4 v[202:203], off
	v_lshl_add_u64 v[202:203], s[38:39], 0, v[0:1]
	s_mov_b32 m0, s42
	s_nop 0
	global_load_lds_dwordx4 v[202:203], off
	s_mov_b32 m0, s43
	s_nop 0
	global_load_lds_dwordx4 v[204:205], off
	ds_read_b128 v[166:169], v242 offset:16384
	ds_read_b128 v[170:173], v242 offset:17408
	ds_read_b128 v[174:177], v242 offset:18432
	ds_read_b128 v[178:181], v242 offset:19456
	ds_read_b128 v[182:185], v242 offset:20480
	ds_read_b128 v[186:189], v242 offset:21504
	ds_read_b128 v[190:193], v242 offset:22528
	ds_read_b128 v[194:197], v242 offset:23552
	s_waitcnt vmcnt(8)
	s_waitcnt lgkmcnt(0)
	s_barrier
	s_setprio 1
	s_waitcnt lgkmcnt(0)
	v_mfma_f32_16x16x32_bf16 v[66:69], v[70:73], v[166:169], v[66:69]
	v_mfma_f32_16x16x32_bf16 v[62:65], v[78:81], v[166:169], v[62:65]
	v_mfma_f32_16x16x32_bf16 v[50:53], v[70:73], v[174:177], v[50:53]
	v_mfma_f32_16x16x32_bf16 v[46:49], v[78:81], v[174:177], v[46:49]
	v_mfma_f32_16x16x32_bf16 v[34:37], v[70:73], v[182:185], v[34:37]
	v_mfma_f32_16x16x32_bf16 v[30:33], v[78:81], v[182:185], v[30:33]
	v_mfma_f32_16x16x32_bf16 v[18:21], v[70:73], v[190:193], v[18:21]
	v_mfma_f32_16x16x32_bf16 v[10:13], v[78:81], v[190:193], v[10:13]
	v_mfma_f32_16x16x32_bf16 v[66:69], v[74:77], v[170:173], v[66:69]
	v_mfma_f32_16x16x32_bf16 v[62:65], v[82:85], v[170:173], v[62:65]
	v_mfma_f32_16x16x32_bf16 v[50:53], v[74:77], v[178:181], v[50:53]
	v_mfma_f32_16x16x32_bf16 v[46:49], v[82:85], v[178:181], v[46:49]
	v_mfma_f32_16x16x32_bf16 v[34:37], v[74:77], v[186:189], v[34:37]
	v_mfma_f32_16x16x32_bf16 v[30:33], v[82:85], v[186:189], v[30:33]
	v_mfma_f32_16x16x32_bf16 v[18:21], v[74:77], v[194:197], v[18:21]
	v_mfma_f32_16x16x32_bf16 v[10:13], v[82:85], v[194:197], v[10:13]
	s_setprio 0
	s_setprio 1
	v_mfma_f32_16x16x32_bf16 v[58:61], v[150:153], v[166:169], v[58:61]
	v_mfma_f32_16x16x32_bf16 v[54:57], v[158:161], v[166:169], v[54:57]
	v_mfma_f32_16x16x32_bf16 v[42:45], v[150:153], v[174:177], v[42:45]
	v_mfma_f32_16x16x32_bf16 v[38:41], v[158:161], v[174:177], v[38:41]
	v_mfma_f32_16x16x32_bf16 v[26:29], v[150:153], v[182:185], v[26:29]
	v_mfma_f32_16x16x32_bf16 v[22:25], v[158:161], v[182:185], v[22:25]
	v_mfma_f32_16x16x32_bf16 v[6:9], v[150:153], v[190:193], v[6:9]
	v_mfma_f32_16x16x32_bf16 v[2:5], v[158:161], v[190:193], v[2:5]
	v_mfma_f32_16x16x32_bf16 v[58:61], v[154:157], v[170:173], v[58:61]
	v_mfma_f32_16x16x32_bf16 v[54:57], v[162:165], v[170:173], v[54:57]
	v_mfma_f32_16x16x32_bf16 v[42:45], v[154:157], v[178:181], v[42:45]
	v_mfma_f32_16x16x32_bf16 v[38:41], v[162:165], v[178:181], v[38:41]
	v_mfma_f32_16x16x32_bf16 v[26:29], v[154:157], v[186:189], v[26:29]
	v_mfma_f32_16x16x32_bf16 v[22:25], v[162:165], v[186:189], v[22:25]
	v_mfma_f32_16x16x32_bf16 v[6:9], v[154:157], v[194:197], v[6:9]
	v_mfma_f32_16x16x32_bf16 v[2:5], v[162:165], v[194:197], v[2:5]
	s_setprio 0
	s_barrier
	s_add_i32 s3, 0, 0x18000
	s_add_i32 s24, 0, 0x1c000
	s_add_u32 s22, s38, 0xb0000
	s_addc_u32 s23, s39, 0
	s_mov_b32 m0, s44
	v_lshl_add_u64 v[206:207], s[22:23], 0, v[0:1]
	global_load_lds_dwordx4 v[206:207], off
	v_lshl_add_u64 v[206:207], s[22:23], 0, v[14:15]
	s_mov_b32 m0, s45
	s_nop 0
	global_load_lds_dwordx4 v[206:207], off
	v_add_u32_e32 v82, s3, v17
	v_add_u32_e32 v162, s24, v17
	ds_read_b128 v[70:73], v82
	ds_read_b128 v[74:77], v82 offset:1024
	ds_read_b128 v[78:81], v82 offset:2048
	ds_read_b128 v[82:85], v82 offset:3072
	ds_read_b128 v[150:153], v162
	ds_read_b128 v[154:157], v162 offset:1024
	ds_read_b128 v[158:161], v162 offset:2048
	ds_read_b128 v[162:165], v162 offset:3072
	ds_read_b128 v[166:169], v242 offset:32768
	ds_read_b128 v[170:173], v242 offset:33792
	ds_read_b128 v[174:177], v242 offset:34816
	ds_read_b128 v[178:181], v242 offset:35840
	ds_read_b128 v[182:185], v242 offset:36864
	ds_read_b128 v[186:189], v242 offset:37888
	ds_read_b128 v[190:193], v242 offset:38912
	ds_read_b128 v[194:197], v242 offset:39936
	s_waitcnt vmcnt(8)
	s_waitcnt lgkmcnt(0)
	s_barrier
	s_setprio 1
	s_waitcnt lgkmcnt(0)
	v_mfma_f32_16x16x32_bf16 v[146:149], v[70:73], v[166:169], v[146:149]
	v_mfma_f32_16x16x32_bf16 v[142:145], v[78:81], v[166:169], v[142:145]
	v_mfma_f32_16x16x32_bf16 v[130:133], v[70:73], v[174:177], v[130:133]
	v_mfma_f32_16x16x32_bf16 v[126:129], v[78:81], v[174:177], v[126:129]
	v_mfma_f32_16x16x32_bf16 v[114:117], v[70:73], v[182:185], v[114:117]
	v_mfma_f32_16x16x32_bf16 v[110:113], v[78:81], v[182:185], v[110:113]
	v_mfma_f32_16x16x32_bf16 v[98:101], v[70:73], v[190:193], v[98:101]
	v_mfma_f32_16x16x32_bf16 v[94:97], v[78:81], v[190:193], v[94:97]
	v_mfma_f32_16x16x32_bf16 v[146:149], v[74:77], v[170:173], v[146:149]
	v_mfma_f32_16x16x32_bf16 v[142:145], v[82:85], v[170:173], v[142:145]
	v_mfma_f32_16x16x32_bf16 v[130:133], v[74:77], v[178:181], v[130:133]
	v_mfma_f32_16x16x32_bf16 v[126:129], v[82:85], v[178:181], v[126:129]
	v_mfma_f32_16x16x32_bf16 v[114:117], v[74:77], v[186:189], v[114:117]
	v_mfma_f32_16x16x32_bf16 v[110:113], v[82:85], v[186:189], v[110:113]
	v_mfma_f32_16x16x32_bf16 v[98:101], v[74:77], v[194:197], v[98:101]
	v_mfma_f32_16x16x32_bf16 v[94:97], v[82:85], v[194:197], v[94:97]
	s_setprio 0
	s_setprio 1
	v_mfma_f32_16x16x32_bf16 v[138:141], v[150:153], v[166:169], v[138:141]
	v_mfma_f32_16x16x32_bf16 v[134:137], v[158:161], v[166:169], v[134:137]
	v_mfma_f32_16x16x32_bf16 v[122:125], v[150:153], v[174:177], v[122:125]
	v_mfma_f32_16x16x32_bf16 v[118:121], v[158:161], v[174:177], v[118:121]
	v_mfma_f32_16x16x32_bf16 v[106:109], v[150:153], v[182:185], v[106:109]
	v_mfma_f32_16x16x32_bf16 v[102:105], v[158:161], v[182:185], v[102:105]
	v_mfma_f32_16x16x32_bf16 v[90:93], v[150:153], v[190:193], v[90:93]
	v_mfma_f32_16x16x32_bf16 v[86:89], v[158:161], v[190:193], v[86:89]
	v_mfma_f32_16x16x32_bf16 v[138:141], v[154:157], v[170:173], v[138:141]
	v_mfma_f32_16x16x32_bf16 v[134:137], v[162:165], v[170:173], v[134:137]
	v_mfma_f32_16x16x32_bf16 v[122:125], v[154:157], v[178:181], v[122:125]
	v_mfma_f32_16x16x32_bf16 v[118:121], v[162:165], v[178:181], v[118:121]
	v_mfma_f32_16x16x32_bf16 v[106:109], v[154:157], v[186:189], v[106:109]
	v_mfma_f32_16x16x32_bf16 v[102:105], v[162:165], v[186:189], v[102:105]
	v_mfma_f32_16x16x32_bf16 v[90:93], v[154:157], v[194:197], v[90:93]
	v_mfma_f32_16x16x32_bf16 v[86:89], v[162:165], v[194:197], v[86:89]
	s_setprio 0
	s_barrier
	s_add_i32 s3, s3, s41
	v_lshl_add_u64 v[198:199], v[198:199], 0, s[92:93]
	s_mov_b32 m0, s3
	s_nop 0
	global_load_lds_dwordx4 v[198:199], off
	s_add_i32 m0, s3, 0x2000
	s_add_u32 s22, s36, 0xb0080
	v_lshl_add_u64 v[198:199], v[200:201], 0, s[92:93]
	s_addc_u32 s23, s37, 0
	s_add_i32 s3, s24, s41
	global_load_lds_dwordx4 v[198:199], off
	v_lshl_add_u64 v[198:199], s[22:23], 0, v[0:1]
	s_mov_b32 m0, s3
	s_nop 0
	global_load_lds_dwordx4 v[198:199], off
	v_lshl_add_u64 v[198:199], s[22:23], 0, v[14:15]
	s_add_i32 m0, s3, 0x2000
	s_nop 0
	global_load_lds_dwordx4 v[198:199], off
	v_lshl_add_u64 v[198:199], v[202:203], 0, s[92:93]
	s_mov_b32 m0, s50
	s_nop 0
	global_load_lds_dwordx4 v[198:199], off
	v_lshl_add_u64 v[198:199], v[204:205], 0, s[92:93]
	s_mov_b32 m0, s51
	s_nop 0
	global_load_lds_dwordx4 v[198:199], off
	ds_read_b128 v[166:169], v242 offset:49152
	ds_read_b128 v[170:173], v242 offset:50176
	ds_read_b128 v[174:177], v242 offset:51200
	ds_read_b128 v[178:181], v242 offset:52224
	ds_read_b128 v[182:185], v242 offset:53248
	ds_read_b128 v[186:189], v242 offset:54272
	ds_read_b128 v[190:193], v242 offset:55296
	ds_read_b128 v[194:197], v242 offset:56320
	s_waitcnt vmcnt(8)
	s_waitcnt lgkmcnt(0)
	s_barrier
	s_setprio 1
	s_waitcnt lgkmcnt(0)
	v_mfma_f32_16x16x32_bf16 v[66:69], v[70:73], v[166:169], v[66:69]
	v_mfma_f32_16x16x32_bf16 v[62:65], v[78:81], v[166:169], v[62:65]
	v_mfma_f32_16x16x32_bf16 v[50:53], v[70:73], v[174:177], v[50:53]
	v_mfma_f32_16x16x32_bf16 v[46:49], v[78:81], v[174:177], v[46:49]
	v_mfma_f32_16x16x32_bf16 v[34:37], v[70:73], v[182:185], v[34:37]
	v_mfma_f32_16x16x32_bf16 v[30:33], v[78:81], v[182:185], v[30:33]
	v_mfma_f32_16x16x32_bf16 v[18:21], v[70:73], v[190:193], v[18:21]
	v_mfma_f32_16x16x32_bf16 v[10:13], v[78:81], v[190:193], v[10:13]
	v_mfma_f32_16x16x32_bf16 v[66:69], v[74:77], v[170:173], v[66:69]
	v_mfma_f32_16x16x32_bf16 v[62:65], v[82:85], v[170:173], v[62:65]
	v_mfma_f32_16x16x32_bf16 v[50:53], v[74:77], v[178:181], v[50:53]
	v_mfma_f32_16x16x32_bf16 v[46:49], v[82:85], v[178:181], v[46:49]
	v_mfma_f32_16x16x32_bf16 v[34:37], v[74:77], v[186:189], v[34:37]
	v_mfma_f32_16x16x32_bf16 v[30:33], v[82:85], v[186:189], v[30:33]
	v_mfma_f32_16x16x32_bf16 v[18:21], v[74:77], v[194:197], v[18:21]
	v_mfma_f32_16x16x32_bf16 v[10:13], v[82:85], v[194:197], v[10:13]
	s_setprio 0
	s_setprio 1
	v_mfma_f32_16x16x32_bf16 v[58:61], v[150:153], v[166:169], v[58:61]
	v_mfma_f32_16x16x32_bf16 v[54:57], v[158:161], v[166:169], v[54:57]
	v_mfma_f32_16x16x32_bf16 v[42:45], v[150:153], v[174:177], v[42:45]
	v_mfma_f32_16x16x32_bf16 v[38:41], v[158:161], v[174:177], v[38:41]
	v_mfma_f32_16x16x32_bf16 v[26:29], v[150:153], v[182:185], v[26:29]
	v_mfma_f32_16x16x32_bf16 v[22:25], v[158:161], v[182:185], v[22:25]
	v_mfma_f32_16x16x32_bf16 v[6:9], v[150:153], v[190:193], v[6:9]
	v_mfma_f32_16x16x32_bf16 v[2:5], v[158:161], v[190:193], v[2:5]
	v_mfma_f32_16x16x32_bf16 v[58:61], v[154:157], v[170:173], v[58:61]
	v_mfma_f32_16x16x32_bf16 v[54:57], v[162:165], v[170:173], v[54:57]
	v_mfma_f32_16x16x32_bf16 v[42:45], v[154:157], v[178:181], v[42:45]
	v_mfma_f32_16x16x32_bf16 v[38:41], v[162:165], v[178:181], v[38:41]
	v_mfma_f32_16x16x32_bf16 v[26:29], v[154:157], v[186:189], v[26:29]
	v_mfma_f32_16x16x32_bf16 v[22:25], v[162:165], v[186:189], v[22:25]
	v_mfma_f32_16x16x32_bf16 v[6:9], v[154:157], v[194:197], v[6:9]
	v_mfma_f32_16x16x32_bf16 v[2:5], v[162:165], v[194:197], v[2:5]
	s_setprio 0
	s_barrier
	s_add_i32 s57, s57, 2
	s_add_u32 s2, s2, 0x100
	s_addc_u32 s55, s55, 0
	s_cmp_gt_u32 s57, 41
	s_mov_b64 s[22:23], s[6:7]
	s_cbranch_scc0 .LBB0_751
	s_and_b64 vcc, exec, s[12:13]
	s_cbranch_vccz .LBB0_754
	s_barrier

.LBB0_817:
	s_add_u32 s3, s36, 0xfffc0080
	s_addc_u32 s24, s37, -1
	s_cmp_eq_u32 s50, 12
	s_cselect_b32 s41, s17, s24
	s_cselect_b32 s40, s47, s3
	s_cselect_b32 s39, s2, s49
	s_cselect_b32 s38, s15, s48
	s_add_i32 s3, 0, 0x14000
	v_lshl_add_u64 v[208:209], s[36:37], 0, v[154:155]
	s_add_i32 m0, s28, 0xc000
	s_nop 0
	global_load_lds_dwordx4 v[208:209], off
	v_lshl_add_u64 v[208:209], s[36:37], 0, v[156:157]
	s_add_i32 m0, s28, 0xe000
	s_nop 0
	global_load_lds_dwordx4 v[208:209], off
	v_add_u32_e32 v146, s63, v17
	v_add_u32_e32 v170, s3, v17
	ds_read_b128 v[134:137], v146
	ds_read_b128 v[138:141], v146 offset:1024
	ds_read_b128 v[142:145], v146 offset:2048
	ds_read_b128 v[146:149], v146 offset:3072
	ds_read_b128 v[158:161], v170
	ds_read_b128 v[162:165], v170 offset:1024
	ds_read_b128 v[166:169], v170 offset:2048
	ds_read_b128 v[170:173], v170 offset:3072
	ds_read_b128 v[174:177], v182
	ds_read_b128 v[178:181], v182 offset:1024
	ds_read_b128 v[184:187], v182 offset:2048
	ds_read_b128 v[188:191], v182 offset:3072
	ds_read_b128 v[192:195], v182 offset:4096
	ds_read_b128 v[196:199], v182 offset:5120
	ds_read_b128 v[200:203], v182 offset:6144
	ds_read_b128 v[204:207], v182 offset:7168
	s_waitcnt vmcnt(8)
	s_waitcnt lgkmcnt(0)
	s_barrier
	s_setprio 1
	s_waitcnt lgkmcnt(0)
	v_mfma_f32_16x16x32_bf16 v[130:133], v[134:137], v[174:177], v[130:133]
	v_mfma_f32_16x16x32_bf16 v[126:129], v[142:145], v[174:177], v[126:129]
	v_mfma_f32_16x16x32_bf16 v[114:117], v[134:137], v[184:187], v[114:117]
	v_mfma_f32_16x16x32_bf16 v[110:113], v[142:145], v[184:187], v[110:113]
	v_mfma_f32_16x16x32_bf16 v[98:101], v[134:137], v[192:195], v[98:101]
	v_mfma_f32_16x16x32_bf16 v[94:97], v[142:145], v[192:195], v[94:97]
	v_mfma_f32_16x16x32_bf16 v[82:85], v[134:137], v[200:203], v[82:85]
	v_mfma_f32_16x16x32_bf16 v[78:81], v[142:145], v[200:203], v[78:81]
	v_mfma_f32_16x16x32_bf16 v[130:133], v[138:141], v[178:181], v[130:133]
	v_mfma_f32_16x16x32_bf16 v[126:129], v[146:149], v[178:181], v[126:129]
	v_mfma_f32_16x16x32_bf16 v[114:117], v[138:141], v[188:191], v[114:117]
	v_mfma_f32_16x16x32_bf16 v[110:113], v[146:149], v[188:191], v[110:113]
	v_mfma_f32_16x16x32_bf16 v[98:101], v[138:141], v[196:199], v[98:101]
	v_mfma_f32_16x16x32_bf16 v[94:97], v[146:149], v[196:199], v[94:97]
	v_mfma_f32_16x16x32_bf16 v[82:85], v[138:141], v[204:207], v[82:85]
	v_mfma_f32_16x16x32_bf16 v[78:81], v[146:149], v[204:207], v[78:81]
	s_setprio 0
	s_setprio 1
	v_mfma_f32_16x16x32_bf16 v[122:125], v[158:161], v[174:177], v[122:125]
	v_mfma_f32_16x16x32_bf16 v[118:121], v[166:169], v[174:177], v[118:121]
	v_mfma_f32_16x16x32_bf16 v[106:109], v[158:161], v[184:187], v[106:109]
	v_mfma_f32_16x16x32_bf16 v[102:105], v[166:169], v[184:187], v[102:105]
	v_mfma_f32_16x16x32_bf16 v[90:93], v[158:161], v[192:195], v[90:93]
	v_mfma_f32_16x16x32_bf16 v[86:89], v[166:169], v[192:195], v[86:89]
	v_mfma_f32_16x16x32_bf16 v[74:77], v[158:161], v[200:203], v[74:77]
	v_mfma_f32_16x16x32_bf16 v[70:73], v[166:169], v[200:203], v[70:73]
	v_mfma_f32_16x16x32_bf16 v[122:125], v[162:165], v[178:181], v[122:125]
	v_mfma_f32_16x16x32_bf16 v[118:121], v[170:173], v[178:181], v[118:121]
	v_mfma_f32_16x16x32_bf16 v[106:109], v[162:165], v[188:191], v[106:109]
	v_mfma_f32_16x16x32_bf16 v[102:105], v[170:173], v[188:191], v[102:105]
	v_mfma_f32_16x16x32_bf16 v[90:93], v[162:165], v[196:199], v[90:93]
	v_mfma_f32_16x16x32_bf16 v[86:89], v[170:173], v[196:199], v[86:89]
	v_mfma_f32_16x16x32_bf16 v[74:77], v[162:165], v[204:207], v[74:77]
	v_mfma_f32_16x16x32_bf16 v[70:73], v[170:173], v[204:207], v[70:73]
	s_setprio 0
	s_barrier
	s_add_i32 s24, s63, s1
	v_lshl_add_u64 v[208:209], s[38:39], 0, v[0:1]
	s_mov_b32 m0, s24
	s_nop 0
	global_load_lds_dwordx4 v[208:209], off
	s_add_i32 m0, s24, 0x2000
	s_add_u32 s24, s38, 0x40000
	v_lshl_add_u64 v[210:211], s[38:39], 0, v[14:15]
	s_addc_u32 s25, s39, 0
	s_add_i32 s3, s3, s1
	global_load_lds_dwordx4 v[210:211], off
	v_lshl_add_u64 v[212:213], s[24:25], 0, v[0:1]
	s_mov_b32 m0, s3
	v_lshl_add_u64 v[218:219], s[40:41], 0, v[150:151]
	global_load_lds_dwordx4 v[212:213], off
	v_lshl_add_u64 v[212:213], s[24:25], 0, v[14:15]
	s_add_i32 m0, s3, 0x2000
	s_nop 0
	global_load_lds_dwordx4 v[212:213], off
	v_lshl_add_u64 v[212:213], s[40:41], 0, v[152:153]
	s_mov_b32 m0, s28
	s_nop 0
	global_load_lds_dwordx4 v[212:213], off
	s_mov_b32 m0, s29
	s_nop 0
	global_load_lds_dwordx4 v[218:219], off
	ds_read_b128 v[174:177], v182 offset:16384
	ds_read_b128 v[178:181], v182 offset:17408
	ds_read_b128 v[184:187], v182 offset:18432
	ds_read_b128 v[188:191], v182 offset:19456
	ds_read_b128 v[192:195], v182 offset:20480
	ds_read_b128 v[196:199], v182 offset:21504
	ds_read_b128 v[200:203], v182 offset:22528
	ds_read_b128 v[204:207], v182 offset:23552
	s_waitcnt vmcnt(8)
	s_waitcnt lgkmcnt(0)
	s_barrier
	s_setprio 1
	s_waitcnt lgkmcnt(0)
	v_mfma_f32_16x16x32_bf16 v[66:69], v[134:137], v[174:177], v[66:69]
	v_mfma_f32_16x16x32_bf16 v[62:65], v[142:145], v[174:177], v[62:65]
	v_mfma_f32_16x16x32_bf16 v[50:53], v[134:137], v[184:187], v[50:53]
	v_mfma_f32_16x16x32_bf16 v[46:49], v[142:145], v[184:187], v[46:49]
	v_mfma_f32_16x16x32_bf16 v[34:37], v[134:137], v[192:195], v[34:37]
	v_mfma_f32_16x16x32_bf16 v[30:33], v[142:145], v[192:195], v[30:33]
	v_mfma_f32_16x16x32_bf16 v[18:21], v[134:137], v[200:203], v[18:21]
	v_mfma_f32_16x16x32_bf16 v[10:13], v[142:145], v[200:203], v[10:13]
	v_mfma_f32_16x16x32_bf16 v[66:69], v[138:141], v[178:181], v[66:69]
	v_mfma_f32_16x16x32_bf16 v[62:65], v[146:149], v[178:181], v[62:65]
	v_mfma_f32_16x16x32_bf16 v[50:53], v[138:141], v[188:191], v[50:53]
	v_mfma_f32_16x16x32_bf16 v[46:49], v[146:149], v[188:191], v[46:49]
	v_mfma_f32_16x16x32_bf16 v[34:37], v[138:141], v[196:199], v[34:37]
	v_mfma_f32_16x16x32_bf16 v[30:33], v[146:149], v[196:199], v[30:33]
	v_mfma_f32_16x16x32_bf16 v[18:21], v[138:141], v[204:207], v[18:21]
	v_mfma_f32_16x16x32_bf16 v[10:13], v[146:149], v[204:207], v[10:13]
	s_setprio 0
	s_setprio 1
	v_mfma_f32_16x16x32_bf16 v[58:61], v[158:161], v[174:177], v[58:61]
	v_mfma_f32_16x16x32_bf16 v[54:57], v[166:169], v[174:177], v[54:57]
	v_mfma_f32_16x16x32_bf16 v[42:45], v[158:161], v[184:187], v[42:45]
	v_mfma_f32_16x16x32_bf16 v[38:41], v[166:169], v[184:187], v[38:41]
	v_mfma_f32_16x16x32_bf16 v[26:29], v[158:161], v[192:195], v[26:29]
	v_mfma_f32_16x16x32_bf16 v[22:25], v[166:169], v[192:195], v[22:25]
	v_mfma_f32_16x16x32_bf16 v[6:9], v[158:161], v[200:203], v[6:9]
	v_mfma_f32_16x16x32_bf16 v[2:5], v[166:169], v[200:203], v[2:5]
	v_mfma_f32_16x16x32_bf16 v[58:61], v[162:165], v[178:181], v[58:61]
	v_mfma_f32_16x16x32_bf16 v[54:57], v[170:173], v[178:181], v[54:57]
	v_mfma_f32_16x16x32_bf16 v[42:45], v[162:165], v[188:191], v[42:45]
	v_mfma_f32_16x16x32_bf16 v[38:41], v[170:173], v[188:191], v[38:41]
	v_mfma_f32_16x16x32_bf16 v[26:29], v[162:165], v[196:199], v[26:29]
	v_mfma_f32_16x16x32_bf16 v[22:25], v[170:173], v[196:199], v[22:25]
	v_mfma_f32_16x16x32_bf16 v[6:9], v[162:165], v[204:207], v[6:9]
	v_mfma_f32_16x16x32_bf16 v[2:5], v[170:173], v[204:207], v[2:5]
	s_setprio 0
	s_barrier
	s_add_i32 s3, 0, 0x18000
	s_add_i32 s26, 0, 0x1c000
	s_add_u32 s24, s40, 0x40000
	s_addc_u32 s25, s41, 0
	s_mov_b32 m0, s42
	v_lshl_add_u64 v[220:221], s[24:25], 0, v[152:153]
	global_load_lds_dwordx4 v[220:221], off
	v_lshl_add_u64 v[220:221], s[24:25], 0, v[150:151]
	s_mov_b32 m0, s43
	s_nop 0
	global_load_lds_dwordx4 v[220:221], off
	v_add_u32_e32 v146, s3, v17
	v_add_u32_e32 v170, s26, v17
	ds_read_b128 v[134:137], v146
	ds_read_b128 v[138:141], v146 offset:1024
	ds_read_b128 v[142:145], v146 offset:2048
	ds_read_b128 v[146:149], v146 offset:3072
	ds_read_b128 v[158:161], v170
	ds_read_b128 v[162:165], v170 offset:1024
	ds_read_b128 v[166:169], v170 offset:2048
	ds_read_b128 v[170:173], v170 offset:3072
	ds_read_b128 v[174:177], v182 offset:32768
	ds_read_b128 v[178:181], v182 offset:33792
	ds_read_b128 v[184:187], v182 offset:34816
	ds_read_b128 v[188:191], v182 offset:35840
	ds_read_b128 v[192:195], v182 offset:36864
	ds_read_b128 v[196:199], v182 offset:37888
	ds_read_b128 v[200:203], v182 offset:38912
	ds_read_b128 v[204:207], v182 offset:39936
	s_waitcnt vmcnt(8)
	s_waitcnt lgkmcnt(0)
	s_barrier
	s_setprio 1
	s_waitcnt lgkmcnt(0)
	v_mfma_f32_16x16x32_bf16 v[130:133], v[134:137], v[174:177], v[130:133]
	v_mfma_f32_16x16x32_bf16 v[126:129], v[142:145], v[174:177], v[126:129]
	v_mfma_f32_16x16x32_bf16 v[114:117], v[134:137], v[184:187], v[114:117]
	v_mfma_f32_16x16x32_bf16 v[110:113], v[142:145], v[184:187], v[110:113]
	v_mfma_f32_16x16x32_bf16 v[98:101], v[134:137], v[192:195], v[98:101]
	v_mfma_f32_16x16x32_bf16 v[94:97], v[142:145], v[192:195], v[94:97]
	v_mfma_f32_16x16x32_bf16 v[82:85], v[134:137], v[200:203], v[82:85]
	v_mfma_f32_16x16x32_bf16 v[78:81], v[142:145], v[200:203], v[78:81]
	v_mfma_f32_16x16x32_bf16 v[130:133], v[138:141], v[178:181], v[130:133]
	v_mfma_f32_16x16x32_bf16 v[126:129], v[146:149], v[178:181], v[126:129]
	v_mfma_f32_16x16x32_bf16 v[114:117], v[138:141], v[188:191], v[114:117]
	v_mfma_f32_16x16x32_bf16 v[110:113], v[146:149], v[188:191], v[110:113]
	v_mfma_f32_16x16x32_bf16 v[98:101], v[138:141], v[196:199], v[98:101]
	v_mfma_f32_16x16x32_bf16 v[94:97], v[146:149], v[196:199], v[94:97]
	v_mfma_f32_16x16x32_bf16 v[82:85], v[138:141], v[204:207], v[82:85]
	v_mfma_f32_16x16x32_bf16 v[78:81], v[146:149], v[204:207], v[78:81]
	s_setprio 0
	s_setprio 1
	v_mfma_f32_16x16x32_bf16 v[122:125], v[158:161], v[174:177], v[122:125]
	v_mfma_f32_16x16x32_bf16 v[118:121], v[166:169], v[174:177], v[118:121]
	v_mfma_f32_16x16x32_bf16 v[106:109], v[158:161], v[184:187], v[106:109]
	v_mfma_f32_16x16x32_bf16 v[102:105], v[166:169], v[184:187], v[102:105]
	v_mfma_f32_16x16x32_bf16 v[90:93], v[158:161], v[192:195], v[90:93]
	v_mfma_f32_16x16x32_bf16 v[86:89], v[166:169], v[192:195], v[86:89]
	v_mfma_f32_16x16x32_bf16 v[74:77], v[158:161], v[200:203], v[74:77]
	v_mfma_f32_16x16x32_bf16 v[70:73], v[166:169], v[200:203], v[70:73]
	v_mfma_f32_16x16x32_bf16 v[122:125], v[162:165], v[178:181], v[122:125]
	v_mfma_f32_16x16x32_bf16 v[118:121], v[170:173], v[178:181], v[118:121]
	v_mfma_f32_16x16x32_bf16 v[106:109], v[162:165], v[188:191], v[106:109]
	v_mfma_f32_16x16x32_bf16 v[102:105], v[170:173], v[188:191], v[102:105]
	v_mfma_f32_16x16x32_bf16 v[90:93], v[162:165], v[196:199], v[90:93]
	v_mfma_f32_16x16x32_bf16 v[86:89], v[170:173], v[196:199], v[86:89]
	v_mfma_f32_16x16x32_bf16 v[74:77], v[162:165], v[204:207], v[74:77]
	v_mfma_f32_16x16x32_bf16 v[70:73], v[170:173], v[204:207], v[70:73]
	s_setprio 0
	s_barrier
	s_add_i32 s3, s3, s1
	v_lshl_add_u64 v[208:209], v[208:209], 0, s[92:93]
	s_mov_b32 m0, s3
	s_nop 0
	global_load_lds_dwordx4 v[208:209], off
	s_add_i32 m0, s3, 0x2000
	s_add_u32 s24, s38, 0x40080
	v_lshl_add_u64 v[208:209], v[210:211], 0, s[92:93]
	s_addc_u32 s25, s39, 0
	s_add_i32 s3, s26, s1
	global_load_lds_dwordx4 v[208:209], off
	v_lshl_add_u64 v[208:209], s[24:25], 0, v[0:1]
	s_mov_b32 m0, s3
	s_nop 0
	global_load_lds_dwordx4 v[208:209], off
	v_lshl_add_u64 v[208:209], s[24:25], 0, v[14:15]
	s_add_i32 m0, s3, 0x2000
	s_nop 0
	global_load_lds_dwordx4 v[208:209], off
	v_lshl_add_u64 v[208:209], v[212:213], 0, s[92:93]
	s_mov_b32 m0, s44
	s_nop 0
	global_load_lds_dwordx4 v[208:209], off
	v_lshl_add_u64 v[208:209], v[218:219], 0, s[92:93]
	s_mov_b32 m0, s45
	s_nop 0
	global_load_lds_dwordx4 v[208:209], off
	ds_read_b128 v[174:177], v182 offset:49152
	ds_read_b128 v[178:181], v182 offset:50176
	ds_read_b128 v[184:187], v182 offset:51200
	ds_read_b128 v[188:191], v182 offset:52224
	ds_read_b128 v[192:195], v182 offset:53248
	ds_read_b128 v[196:199], v182 offset:54272
	ds_read_b128 v[200:203], v182 offset:55296
	ds_read_b128 v[204:207], v182 offset:56320
	s_waitcnt vmcnt(8)
	s_waitcnt lgkmcnt(0)
	s_barrier
	s_setprio 1
	s_waitcnt lgkmcnt(0)
	v_mfma_f32_16x16x32_bf16 v[66:69], v[134:137], v[174:177], v[66:69]
	v_mfma_f32_16x16x32_bf16 v[62:65], v[142:145], v[174:177], v[62:65]
	v_mfma_f32_16x16x32_bf16 v[50:53], v[134:137], v[184:187], v[50:53]
	v_mfma_f32_16x16x32_bf16 v[46:49], v[142:145], v[184:187], v[46:49]
	v_mfma_f32_16x16x32_bf16 v[34:37], v[134:137], v[192:195], v[34:37]
	v_mfma_f32_16x16x32_bf16 v[30:33], v[142:145], v[192:195], v[30:33]
	v_mfma_f32_16x16x32_bf16 v[18:21], v[134:137], v[200:203], v[18:21]
	v_mfma_f32_16x16x32_bf16 v[10:13], v[142:145], v[200:203], v[10:13]
	v_mfma_f32_16x16x32_bf16 v[66:69], v[138:141], v[178:181], v[66:69]
	v_mfma_f32_16x16x32_bf16 v[62:65], v[146:149], v[178:181], v[62:65]
	v_mfma_f32_16x16x32_bf16 v[50:53], v[138:141], v[188:191], v[50:53]
	v_mfma_f32_16x16x32_bf16 v[46:49], v[146:149], v[188:191], v[46:49]
	v_mfma_f32_16x16x32_bf16 v[34:37], v[138:141], v[196:199], v[34:37]
	v_mfma_f32_16x16x32_bf16 v[30:33], v[146:149], v[196:199], v[30:33]
	v_mfma_f32_16x16x32_bf16 v[18:21], v[138:141], v[204:207], v[18:21]
	v_mfma_f32_16x16x32_bf16 v[10:13], v[146:149], v[204:207], v[10:13]
	s_setprio 0
	s_setprio 1
	v_mfma_f32_16x16x32_bf16 v[58:61], v[158:161], v[174:177], v[58:61]
	v_mfma_f32_16x16x32_bf16 v[54:57], v[166:169], v[174:177], v[54:57]
	v_mfma_f32_16x16x32_bf16 v[42:45], v[158:161], v[184:187], v[42:45]
	v_mfma_f32_16x16x32_bf16 v[38:41], v[166:169], v[184:187], v[38:41]
	v_mfma_f32_16x16x32_bf16 v[26:29], v[158:161], v[192:195], v[26:29]
	v_mfma_f32_16x16x32_bf16 v[22:25], v[166:169], v[192:195], v[22:25]
	v_mfma_f32_16x16x32_bf16 v[6:9], v[158:161], v[200:203], v[6:9]
	v_mfma_f32_16x16x32_bf16 v[2:5], v[166:169], v[200:203], v[2:5]
	v_mfma_f32_16x16x32_bf16 v[58:61], v[162:165], v[178:181], v[58:61]
	v_mfma_f32_16x16x32_bf16 v[54:57], v[170:173], v[178:181], v[54:57]
	v_mfma_f32_16x16x32_bf16 v[42:45], v[162:165], v[188:191], v[42:45]
	v_mfma_f32_16x16x32_bf16 v[38:41], v[170:173], v[188:191], v[38:41]
	v_mfma_f32_16x16x32_bf16 v[26:29], v[162:165], v[196:199], v[26:29]
	v_mfma_f32_16x16x32_bf16 v[22:25], v[170:173], v[196:199], v[22:25]
	v_mfma_f32_16x16x32_bf16 v[6:9], v[162:165], v[204:207], v[6:9]
	v_mfma_f32_16x16x32_bf16 v[2:5], v[170:173], v[204:207], v[2:5]
	s_setprio 0
	s_barrier
	s_add_i32 s50, s50, 2
	s_add_u32 s36, s36, 0x100
	s_addc_u32 s37, s37, 0
	s_add_u32 s48, s48, 0x100
	s_addc_u32 s49, s49, 0
	s_cmp_gt_u32 s50, 13
	s_cbranch_scc0 .LBB0_817
	s_and_b64 vcc, exec, s[12:13]
	s_cbranch_vccz .LBB0_820
	s_barrier
